# P1 prologue: shift/scale table build batched (40 loads in flight per batch instead of 48 serial 5-load round trips), stacked
# speedup vs baseline: 1.0008x; 1.0008x over previous
.LBB0_190:
	s_cmp_lt_i32 s30, 2
	s_cselect_b64 s[4:5], -1, 0
	s_cmp_gt_i32 s31, 1
	s_cselect_b64 s[6:7], -1, 0
	s_and_b64 s[4:5], s[4:5], s[6:7]
	s_andn2_b64 vcc, exec, s[4:5]
	s_cbranch_vccnz .LBB0_280
	s_mov_b64 s[10:11], s[0:1]
	s_load_dwordx2 s[8:9], s[10:11], 0xe0
	v_mov_b32_e32 v66, v0
	s_movk_i32 s4, 0x6000
	s_waitcnt lgkmcnt(0)
	s_add_u32 s6, s8, 0x100000
	v_readfirstlane_b32 s3, v66
	v_cmp_gt_i32_e32 vcc, s4, v66
	s_addc_u32 s7, s9, 0
	s_and_saveexec_b64 s[12:13], vcc
	s_cbranch_execz .LBB0_198
	s_load_dwordx2 s[14:15], s[10:11], 0x38
	v_lshl_add_u32 v1, v66, 2, 0
	s_mov_b32 s62, 0
	s_waitcnt lgkmcnt(0)
.Lp1_mods:
	s_lshr_b32 s63, s62, 4
	s_and_b32 s64, s62, 15
	s_lshl_b32 s65, s64, 11
	v_add_u32_e32 v176, s65, v1
	s_mul_i32 s66, s63, 0x18000
	s_add_i32 s67, s66, 0x48000
	s_add_i32 s68, s66, 0x90000
	s_add_i32 s69, s66, 0xd8000
	s_lshl_b32 s70, s63, 14
	s_add_i32 s70, s70, s65
	s_cmp_ge_u32 s64, 8
	s_cselect_b32 s71, 0x8000, 0
	s_add_i32 s70, s70, s71
	v_add_u32_e32 v197, s70, v1
	v_mov_b32_e32 v177, v176
	v_add_u32_e32 v178, 0x1000, v176
	v_add_u32_e32 v179, 0x2000, v176
	v_add_u32_e32 v180, 0x3000, v176
	v_add_u32_e32 v181, s66, v177
	v_add_u32_e32 v182, s67, v177
	v_add_u32_e32 v183, s68, v177
	v_add_u32_e32 v184, s69, v177
	v_add_u32_e32 v185, s66, v178
	v_add_u32_e32 v186, s67, v178
	v_add_u32_e32 v187, s68, v178
	v_add_u32_e32 v188, s69, v178
	v_add_u32_e32 v189, s66, v179
	v_add_u32_e32 v190, s67, v179
	v_add_u32_e32 v191, s68, v179
	v_add_u32_e32 v192, s69, v179
	v_add_u32_e32 v193, s66, v180
	v_add_u32_e32 v194, s67, v180
	v_add_u32_e32 v195, s68, v180
	v_add_u32_e32 v196, s69, v180
	global_load_dword v200, v177, s[14:15]
	global_load_dword v208, v181, s[6:7]
	global_load_dword v216, v182, s[6:7]
	global_load_dword v224, v183, s[6:7]
	global_load_dword v232, v184, s[6:7]
	global_load_dword v201, v177, s[14:15] offset:2048
	global_load_dword v209, v181, s[6:7] offset:2048
	global_load_dword v217, v182, s[6:7] offset:2048
	global_load_dword v225, v183, s[6:7] offset:2048
	global_load_dword v233, v184, s[6:7] offset:2048
	global_load_dword v202, v178, s[14:15]
	global_load_dword v210, v185, s[6:7]
	global_load_dword v218, v186, s[6:7]
	global_load_dword v226, v187, s[6:7]
	global_load_dword v234, v188, s[6:7]
	global_load_dword v203, v178, s[14:15] offset:2048
	global_load_dword v211, v185, s[6:7] offset:2048
	global_load_dword v219, v186, s[6:7] offset:2048
	global_load_dword v227, v187, s[6:7] offset:2048
	global_load_dword v235, v188, s[6:7] offset:2048
	global_load_dword v204, v179, s[14:15]
	global_load_dword v212, v189, s[6:7]
	global_load_dword v220, v190, s[6:7]
	global_load_dword v228, v191, s[6:7]
	global_load_dword v236, v192, s[6:7]
	global_load_dword v205, v179, s[14:15] offset:2048
	global_load_dword v213, v189, s[6:7] offset:2048
	global_load_dword v221, v190, s[6:7] offset:2048
	global_load_dword v229, v191, s[6:7] offset:2048
	global_load_dword v237, v192, s[6:7] offset:2048
	global_load_dword v206, v180, s[14:15]
	global_load_dword v214, v193, s[6:7]
	global_load_dword v222, v194, s[6:7]
	global_load_dword v230, v195, s[6:7]
	global_load_dword v238, v196, s[6:7]
	global_load_dword v207, v180, s[14:15] offset:2048
	global_load_dword v215, v193, s[6:7] offset:2048
	global_load_dword v223, v194, s[6:7] offset:2048
	global_load_dword v231, v195, s[6:7] offset:2048
	global_load_dword v239, v196, s[6:7] offset:2048
	s_waitcnt vmcnt(0)
	v_add_f32_e32 v200, v200, v208
	v_add_f32_e32 v200, v200, v216
	v_add_f32_e32 v200, v200, v224
	v_add_f32_e32 v200, v200, v232
	ds_write_b32 v197, v200
	v_add_f32_e32 v201, v201, v209
	v_add_f32_e32 v201, v201, v217
	v_add_f32_e32 v201, v201, v225
	v_add_f32_e32 v201, v201, v233
	ds_write_b32 v197, v201 offset:2048
	v_add_f32_e32 v202, v202, v210
	v_add_f32_e32 v202, v202, v218
	v_add_f32_e32 v202, v202, v226
	v_add_f32_e32 v202, v202, v234
	ds_write_b32 v197, v202 offset:4096
	v_add_f32_e32 v203, v203, v211
	v_add_f32_e32 v203, v203, v219
	v_add_f32_e32 v203, v203, v227
	v_add_f32_e32 v203, v203, v235
	ds_write_b32 v197, v203 offset:6144
	v_add_f32_e32 v204, v204, v212
	v_add_f32_e32 v204, v204, v220
	v_add_f32_e32 v204, v204, v228
	v_add_f32_e32 v204, v204, v236
	ds_write_b32 v197, v204 offset:8192
	v_add_f32_e32 v205, v205, v213
	v_add_f32_e32 v205, v205, v221
	v_add_f32_e32 v205, v205, v229
	v_add_f32_e32 v205, v205, v237
	ds_write_b32 v197, v205 offset:10240
	v_add_f32_e32 v206, v206, v214
	v_add_f32_e32 v206, v206, v222
	v_add_f32_e32 v206, v206, v230
	v_add_f32_e32 v206, v206, v238
	ds_write_b32 v197, v206 offset:12288
	v_add_f32_e32 v207, v207, v215
	v_add_f32_e32 v207, v207, v223
	v_add_f32_e32 v207, v207, v231
	v_add_f32_e32 v207, v207, v239
	ds_write_b32 v197, v207 offset:14336
	s_add_i32 s62, s62, 8
	s_cmp_lt_u32 s62, 48
	s_cbranch_scc1 .Lp1_mods
